# adds: ret_kv next-item loads prefetched before MFMA/stores (constant row delta between a WG's consecutive items)
# baseline (speedup 1.0000x reference)
; __device__ __forceinline__ float bflo(unsigned w) { return __uint_as_float(w << 16); }
; __device__ __forceinline__ float bfhi(unsigned w) { return __uint_as_float(w & 0xffff0000u); }
; __device__ __forceinline__ bf16 f2bf(float f) { return (bf16)(pk2(f, 0.f) & 0xffffu); }
; __device__ __forceinline__ float ex2f(float x) { return __builtin_amdgcn_exp2f(x); }
; __device__ __forceinline__ void ret_kv_item(LAS unsigned char* lds, const bf16* Z, bf16* AT, int b, int c, int hh, float lg) {
;     ...
;     const int tid_ = my_tid(lds); const int tid = tid_, lane = tid & 63, r32 = lane & 31, hi = lane >> 5; const int wid = __builtin_amdgcn_readfirstlane(tid >> 6);
;     const int rowbase = b * SEQ + 64 * c;
; #pragma unroll
;     for (int i = 0; i < 2; ++i) { const int ci = tid + 512 * i, l = ci & 63, dc = ci >> 6; const bf16* zr = Z + (size_t)(rowbase + l) * NZ + hh * 128 + dc * 8;
;         const u32x4 kr = *(const u32x4*)(zr + ZC_RK), vr = *(const u32x4*)(zr + ZC_RV); const float dec = ex2f((float)(63 - l) * lg);
; #pragma unroll
;         for (int e = 0; e < 4; ++e) { const unsigned kw = kr[e], vw = vr[e]; const int d = 8 * dc + 2 * e;
;             KT[d * 72 + l] = f2bf(bflo(kw) * dec); KT[(d + 1) * 72 + l] = f2bf(bfhi(kw) * dec);
;             VTt[d * 72 + l] = (bf16)(vw & 0xffffu); VTt[(d + 1) * 72 + l] = (bf16)(vw >> 16); } }
;     __syncthreads();
; __global__ void __launch_bounds__(512, 2) mega_fwd(Params p) {
;     ...
;           for (int it = vcu; it < 2 * 256 * 4; it += G) { const int hh = it & 3, c = (it >> 2) & 255, b = it >> 10; ret_kv_item(lds, Z, AT, b, c, hh, lgs[hh]); } }
.LBB0_438:
	s_add_i32 s0, 0, 0x258f8
	v_mov_b32_e32 v2, s0
	ds_read_b64 v[0:1], v2
	ds_read_b64 v[2:3], v2
	s_mov_b32 s3, 0
	s_cmpk_gt_i32 s54, 0x7ff
	s_waitcnt lgkmcnt(0)
	v_readfirstlane_b32 s1, v1
	v_readfirstlane_b32 s4, v0
	v_readfirstlane_b32 s2, v3
	v_readfirstlane_b32 s5, v2
	s_cbranch_scc1 .LBB0_441
	s_add_u32 s8, s4, 0x6800000
	s_addc_u32 s9, s1, 0
	s_add_u32 s1, s5, 0x17e00000
	s_addc_u32 s4, s2, 0
	s_lshl_b32 s5, s54, 4
	s_lshl_b32 s6, s68, 4
	v_mov_b32_e32 v34, 0xbd3b9ca6
	v_mov_b32_e32 v35, 0xbcba1f74
	v_mov_b32_e32 v36, 0xbc3963dd
	v_mov_b32_e32 v37, 0xbbb906ce
	s_movk_i32 s7, 0x1400
	v_mov_b64_e32 v[32:33], s[8:9]
	s_movk_i32 s8, 0x48
	s_movk_i32 s9, 0x90
	s_movk_i32 s10, 0x1000
	s_mov_b32 s11, s54
	s_mov_b32 s100, 0
	s_mul_i32 s98, s68, 0x14000
	s_mov_b32 s99, 0
.LBB0_440:
	s_and_b32 s12, s11, 3
	s_bfe_u32 s13, s11, 0x80002
	s_cmp_eq_u32 s12, 1
	s_cselect_b64 vcc, -1, 0
	s_cmp_lg_u32 s12, 2
	s_getreg_b32 s2, hwreg(HW_REG_HW_ID, 0, 6)
	v_cndmask_b32_e32 v0, v34, v35, vcc
	s_cselect_b64 vcc, -1, 0
	s_cmp_lg_u32 s12, 3
	v_cndmask_b32_e32 v0, v36, v0, vcc
	s_cselect_b64 vcc, -1, 0
	s_lshl_b32 s14, s2, 2
	s_and_b32 s14, s14, 0xfc
	s_add_i32 s14, s14, 0
	s_add_i32 s14, s14, 0x25a00
	v_cndmask_b32_e32 v2, v37, v0, vcc
	v_mov_b32_e32 v0, s14
	ds_read_b32 v3, v0
	s_and_b32 s15, s5, 0xffffc000
	s_lshl_b32 s16, s13, 6
	s_or_b32 s15, s16, s15
	v_mbcnt_lo_u32_b32 v4, -1, 0
	v_mbcnt_hi_u32_b32 v4, -1, v4
	s_lshl_b32 s2, s12, 8
	v_and_b32_e32 v14, 63, v4
	v_bitop3_b32 v0, v4, 63, v4 bitop3:0xc
	v_or_b32_e32 v1, s15, v14
	v_cvt_f32_ubyte0_e32 v6, v0
	v_mad_i64_i32 v[0:1], s[14:15], v1, s7, v[32:33]
	v_lshl_add_u64 v[8:9], v[0:1], 0, s[2:3]
	s_waitcnt lgkmcnt(0)
	v_readfirstlane_b32 s2, v3
	v_mul_f32_e32 v2, v2, v6
	v_and_b32_e32 v5, 31, v4
	v_lshl_add_u32 v0, s2, 6, v4
	v_ashrrev_i32_e32 v1, 3, v0
	v_exp_f32_e32 v17, v2
	v_add_u32_e32 v2, 0x200, v0
	v_readfirstlane_b32 s2, v0
	v_and_b32_e32 v0, -8, v1
	v_bfe_u32 v58, v4, 5, 1
	v_ashrrev_i32_e32 v2, 3, v2
	s_ashr_i32 s14, s2, 7
	v_and_or_b32 v59, s2, 64, v5
	v_ashrrev_i32_e32 v1, 31, v0
	v_add_u32_e32 v15, 0x48, v14
	v_lshlrev_b32_e32 v16, 4, v58
	v_mul_lo_u32 v3, v0, s8
	v_and_b32_e32 v10, -8, v2
	v_lshl_or_b32 v2, s14, 5, v5
	v_mul_u32_u24_e32 v4, 0x90, v59
	v_lshl_add_u64 v[12:13], v[0:1], 1, v[8:9]
	v_or_b32_e32 v18, v3, v14
	v_add_u32_e32 v19, v3, v15
	v_mul_lo_u32 v21, v2, s9
	v_add3_u32 v54, 0, v4, v16
	s_cmp_lg_u32 s100, 0
	s_cbranch_scc1 .Lrk_s1
	global_load_dwordx4 v[68:71], v[12:13], off offset:1856
	global_load_dwordx4 v[72:75], v[12:13], off offset:2880
	v_mov_b64_e32 v[76:77], v[12:13]
.Lrk_s1:
	v_ashrrev_i32_e32 v11, 31, v10
	v_mul_lo_u32 v20, v10, s8
	v_lshl_add_u32 v12, v18, 1, 0
	v_lshl_add_u64 v[8:9], v[10:11], 1, v[8:9]
	s_cmp_lg_u32 s100, 0
	s_cbranch_scc1 .Lrk_s2
	global_load_dwordx4 v[60:63], v[8:9], off offset:1856
	global_load_dwordx4 v[64:67], v[8:9], off offset:2880
	v_mov_b64_e32 v[78:79], v[8:9]
.Lrk_s2:
	v_or_b32_e32 v10, v20, v14
	v_add_u32_e32 v11, v20, v15
	v_add3_u32 v50, 0, v21, v16
	v_lshl_add_u32 v13, v19, 1, 0
	v_lshl_add_u32 v10, v10, 1, 0
	v_lshl_add_u32 v11, v11, 1, 0
	s_and_b32 s2, s11, 0xfffffc00
	s_lshl_b32 s13, s13, 2
	s_or_b32 s2, s13, s2
	s_or_b32 s12, s2, s12
	s_ashr_i32 s13, s12, 31
	s_lshl_b64 s[12:13], s[12:13], 15
	s_add_u32 s12, s1, s12
	s_addc_u32 s13, s4, s13
	s_lshl_b32 s2, s14, 12
	s_add_i32 s11, s11, s68
	s_add_i32 s5, s5, s6
	s_cmpk_gt_i32 s11, 0x7ff
	s_cmp_lg_u32 s100, 0
	s_cbranch_scc1 .Lrk_w1p
	s_waitcnt vmcnt(2) lgkmcnt(0)
	s_branch .Lrk_w1d
.Lrk_w1p:
	s_waitcnt vmcnt(34) lgkmcnt(0)
.Lrk_w1d:
	v_mov_b64_e32 v[0:1], v[68:69]
	v_mov_b64_e32 v[2:3], v[70:71]
	v_mov_b64_e32 v[4:5], v[72:73]
	v_mov_b64_e32 v[6:7], v[74:75]
	ds_write_b16 v12, v4 offset:18432
	ds_write_b16_d16_hi v12, v4 offset:18576
	v_lshlrev_b32_e32 v14, 16, v0
	v_and_b32_e32 v0, 0xffff0000, v0
	v_lshlrev_b32_e32 v4, 16, v1
	v_and_b32_e32 v1, 0xffff0000, v1
	v_lshlrev_b32_e32 v15, 16, v2
	v_and_b32_e32 v2, 0xffff0000, v2
	v_lshlrev_b32_e32 v16, 16, v3
	v_and_b32_e32 v3, 0xffff0000, v3
	v_mul_f32_e32 v14, v17, v14
	v_mul_f32_e32 v0, v17, v0
	v_mul_f32_e32 v4, v17, v4
	v_mul_f32_e32 v1, v17, v1
	v_mul_f32_e32 v15, v17, v15
	v_mul_f32_e32 v2, v17, v2
	v_mul_f32_e32 v16, v17, v16
	v_mul_f32_e32 v3, v17, v3
	v_cvt_pk_bf16_f32 v14, v14, s0
	v_cvt_pk_bf16_f32 v0, v0, s0
	v_cvt_pk_bf16_f32 v4, v4, s0
	v_cvt_pk_bf16_f32 v1, v1, s0
	v_cvt_pk_bf16_f32 v15, v15, s0
	v_cvt_pk_bf16_f32 v2, v2, s0
	v_cvt_pk_bf16_f32 v16, v16, s0
	v_cvt_pk_bf16_f32 v3, v3, s0
	ds_write_b16 v12, v14
	ds_write_b16 v12, v0 offset:144
	ds_write_b16 v12, v4 offset:288
	ds_write_b16 v13, v1 offset:288
	ds_write_b16 v12, v5 offset:18720
	ds_write_b16_d16_hi v13, v5 offset:18720
	ds_write_b16 v12, v15 offset:576
	ds_write_b16 v13, v2 offset:576
	ds_write_b16 v12, v6 offset:19008
	ds_write_b16_d16_hi v13, v6 offset:19008
	ds_write_b16 v12, v16 offset:864
	ds_write_b16 v13, v3 offset:864
	ds_write_b16 v12, v7 offset:19296
	ds_write_b16_d16_hi v13, v7 offset:19296
	s_cmp_lg_u32 s100, 0
	s_cbranch_scc1 .Lrk_w2p
	s_waitcnt vmcnt(0) lgkmcnt(0)
	s_branch .Lrk_w2d
.Lrk_w2p:
	s_waitcnt vmcnt(32) lgkmcnt(0)
; #define LAS __attribute__((address_space(3)))
; __device__ __forceinline__ float bflo(unsigned w) { return __uint_as_float(w << 16); }
; __device__ __forceinline__ float bfhi(unsigned w) { return __uint_as_float(w & 0xffff0000u); }
; __device__ __forceinline__ bf16 f2bf(float f) { return (bf16)(pk2(f, 0.f) & 0xffffu); }
; __device__ __forceinline__ int crow(int r, int hi) { return (r & 3) + 8 * (r >> 2) + 4 * hi; }
; #define MFMA32(a, b, c) __builtin_amdgcn_mfma_f32_32x32x16_bf16((a), (b), (c), 0, 0, 0)
; __device__ __forceinline__ void ret_kv_item(LAS unsigned char* lds, const bf16* Z, bf16* AT, int b, int c, int hh, float lg) {
;     ...
;             KT[d * 72 + l] = f2bf(bflo(kw) * dec); KT[(d + 1) * 72 + l] = f2bf(bfhi(kw) * dec);
;             VTt[d * 72 + l] = (bf16)(vw & 0xffffu); VTt[(d + 1) * 72 + l] = (bf16)(vw >> 16); } }
;     __syncthreads();
;     const int eb = wid >> 1, db0 = 2 * (wid & 1);
;     f32x16 a0, a1;
; #pragma unroll
;     for (int r = 0; r < 16; ++r) { a0[r] = 0.f; a1[r] = 0.f; }
; #pragma unroll
;     for (int ks = 0; ks < 4; ++ks) {
;         const bf16x8 af = *(const LAS bf16x8*)(VTt + (32 * eb + r32) * 72 + 16 * ks + 8 * hi);
;         const bf16x8 b0 = *(const LAS bf16x8*)(KT + (32 * db0 + r32) * 72 + 16 * ks + 8 * hi), b1 = *(const LAS bf16x8*)(KT + (32 * db0 + 32 + r32) * 72 + 16 * ks + 8 * hi);
;         a0 = MFMA32(af, b0, a0); a1 = MFMA32(af, b1, a1);
;     }
;     bf16* o = AT + (size_t)((b * 256 + c) * 4 + hh) * 16384;
; #pragma unroll
;     for (int r = 0; r < 16; ++r) { const int e = 32 * eb + crow(r, hi); o[e * 128 + 32 * db0 + r32] = f2bf(a0[r]); o[e * 128 + 32 * db0 + 32 + r32] = f2bf(a1[r]); }
;     __syncthreads();
.Lrk_w2d:
	v_mov_b64_e32 v[0:1], v[60:61]
	v_mov_b64_e32 v[2:3], v[62:63]
	v_mov_b64_e32 v[4:5], v[64:65]
	v_mov_b64_e32 v[6:7], v[66:67]
	ds_write_b16 v10, v4 offset:18432
	ds_write_b16_d16_hi v10, v4 offset:18576
	v_lshlrev_b32_e32 v8, 16, v0
	v_and_b32_e32 v0, 0xffff0000, v0
	v_lshlrev_b32_e32 v4, 16, v1
	v_and_b32_e32 v1, 0xffff0000, v1
	v_lshlrev_b32_e32 v9, 16, v2
	v_and_b32_e32 v2, 0xffff0000, v2
	v_lshlrev_b32_e32 v12, 16, v3
	v_and_b32_e32 v3, 0xffff0000, v3
	v_mul_f32_e32 v8, v17, v8
	v_mul_f32_e32 v0, v17, v0
	v_mul_f32_e32 v1, v17, v1
	v_mul_f32_e32 v2, v17, v2
	v_mul_f32_e32 v3, v17, v3
	v_mul_f32_e32 v4, v17, v4
	v_mul_f32_e32 v9, v17, v9
	v_mul_f32_e32 v12, v17, v12
	v_cvt_pk_bf16_f32 v8, v8, s0
	v_cvt_pk_bf16_f32 v0, v0, s0
	v_cvt_pk_bf16_f32 v1, v1, s0
	v_cvt_pk_bf16_f32 v2, v2, s0
	v_cvt_pk_bf16_f32 v3, v3, s0
	v_cvt_pk_bf16_f32 v4, v4, s0
	v_cvt_pk_bf16_f32 v9, v9, s0
	v_cvt_pk_bf16_f32 v12, v12, s0
	ds_write_b16 v10, v8
	ds_write_b16 v10, v0 offset:144
	ds_write_b16 v10, v4 offset:288
	ds_write_b16 v11, v1 offset:288
	ds_write_b16 v10, v5 offset:18720
	ds_write_b16_d16_hi v11, v5 offset:18720
	ds_write_b16 v10, v9 offset:576
	ds_write_b16 v11, v2 offset:576
	ds_write_b16 v10, v6 offset:19008
	ds_write_b16_d16_hi v11, v6 offset:19008
	ds_write_b16 v10, v12 offset:864
	ds_write_b16 v11, v3 offset:864
	ds_write_b16 v10, v7 offset:19296
	ds_write_b16_d16_hi v11, v7 offset:19296
	s_cmpk_gt_i32 s11, 0x7ff
	s_cbranch_scc1 .Lrk_nopf
	v_lshl_add_u64 v[76:77], v[76:77], 0, s[98:99]
	v_lshl_add_u64 v[78:79], v[78:79], 0, s[98:99]
	global_load_dwordx4 v[68:71], v[76:77], off offset:1856
	global_load_dwordx4 v[72:75], v[76:77], off offset:2880
	global_load_dwordx4 v[60:63], v[78:79], off offset:1856
	global_load_dwordx4 v[64:67], v[78:79], off offset:2880
	s_mov_b32 s100, 1
.Lrk_nopf:
	s_waitcnt lgkmcnt(0)
	s_barrier
	ds_read_b128 v[16:19], v50 offset:18432
	ds_read_b128 v[0:3], v54
	ds_read_b128 v[38:41], v50 offset:18464
	ds_read_b128 v[42:45], v54 offset:32
	s_waitcnt lgkmcnt(2)
	v_mfma_f32_32x32x16_bf16 v[0:15], v[16:19], v[0:3], 0
	ds_read_b128 v[20:23], v54 offset:4608
	ds_read_b128 v[46:49], v54 offset:4640
	s_waitcnt lgkmcnt(1)
	v_mfma_f32_32x32x16_bf16 v[16:31], v[16:19], v[20:23], 0
	v_mfma_f32_32x32x16_bf16 v[0:15], v[38:41], v[42:45], v[0:15]
	s_waitcnt lgkmcnt(0)
	v_mfma_f32_32x32x16_bf16 v[16:31], v[38:41], v[46:49], v[16:31]
	ds_read_b128 v[38:41], v50 offset:18496
	ds_read_b128 v[42:45], v54 offset:64
	ds_read_b128 v[46:49], v50 offset:18528
	ds_read_b128 v[50:53], v54 offset:96
	s_waitcnt lgkmcnt(2)
	v_mfma_f32_32x32x16_bf16 v[0:15], v[38:41], v[42:45], v[0:15]
	ds_read_b128 v[42:45], v54 offset:4672
	ds_read_b128 v[54:57], v54 offset:4704
	s_waitcnt lgkmcnt(1)
	v_mfma_f32_32x32x16_bf16 v[16:31], v[38:41], v[42:45], v[16:31]
	v_lshlrev_b32_e32 v38, 9, v58
	v_or3_b32 v38, s2, v38, v59
	v_ashrrev_i32_e32 v39, 31, v38
	v_lshl_add_u64 v[38:39], v[38:39], 1, s[12:13]
	v_add_co_u32_e32 v40, vcc, s10, v38
	v_mfma_f32_32x32x16_bf16 v[0:15], v[46:49], v[50:53], v[0:15]
	s_nop 0
	v_addc_co_u32_e32 v41, vcc, 0, v39, vcc
	s_waitcnt lgkmcnt(0)
	v_mfma_f32_32x32x16_bf16 v[16:31], v[46:49], v[54:57], v[16:31]
	s_nop 7
	v_cvt_pk_bf16_f32 v0, v0, s0
	v_cvt_pk_bf16_f32 v1, v1, s0
	v_cvt_pk_bf16_f32 v2, v2, s0
	v_cvt_pk_bf16_f32 v3, v3, s0
	v_cvt_pk_bf16_f32 v4, v4, s0
	v_cvt_pk_bf16_f32 v5, v5, s0
	v_cvt_pk_bf16_f32 v6, v6, s0
	v_cvt_pk_bf16_f32 v16, v16, s0
	v_cvt_pk_bf16_f32 v17, v17, s0
	v_cvt_pk_bf16_f32 v18, v18, s0
	v_cvt_pk_bf16_f32 v19, v19, s0
	v_cvt_pk_bf16_f32 v20, v20, s0
	v_cvt_pk_bf16_f32 v21, v21, s0
	v_cvt_pk_bf16_f32 v22, v22, s0
	v_cvt_pk_bf16_f32 v7, v7, s0
	v_cvt_pk_bf16_f32 v23, v23, s0
	v_cvt_pk_bf16_f32 v8, v8, s0
	v_cvt_pk_bf16_f32 v24, v24, s0
	v_cvt_pk_bf16_f32 v9, v9, s0
	v_cvt_pk_bf16_f32 v25, v25, s0
	v_cvt_pk_bf16_f32 v10, v10, s0
	v_cvt_pk_bf16_f32 v26, v26, s0
	v_cvt_pk_bf16_f32 v11, v11, s0
	v_cvt_pk_bf16_f32 v27, v27, s0
	v_cvt_pk_bf16_f32 v12, v12, s0
	v_cvt_pk_bf16_f32 v28, v28, s0
	v_cvt_pk_bf16_f32 v13, v13, s0
	v_cvt_pk_bf16_f32 v29, v29, s0
	v_cvt_pk_bf16_f32 v14, v14, s0
	v_cvt_pk_bf16_f32 v30, v30, s0
	v_cvt_pk_bf16_f32 v15, v15, s0
	v_cvt_pk_bf16_f32 v31, v31, s0
	global_store_short v[38:39], v0, off
	global_store_short v[38:39], v16, off offset:64
	global_store_short v[38:39], v1, off offset:256
	global_store_short v[38:39], v17, off offset:320
	global_store_short v[38:39], v2, off offset:512
	global_store_short v[38:39], v18, off offset:576
	global_store_short v[38:39], v3, off offset:768
	global_store_short v[38:39], v19, off offset:832
	global_store_short v[38:39], v4, off offset:2048
	global_store_short v[38:39], v20, off offset:2112
	global_store_short v[38:39], v5, off offset:2304
	global_store_short v[38:39], v21, off offset:2368
	global_store_short v[38:39], v6, off offset:2560
	global_store_short v[38:39], v22, off offset:2624
	global_store_short v[38:39], v7, off offset:2816
	global_store_short v[38:39], v23, off offset:2880
	global_store_short v[40:41], v8, off
	global_store_short v[40:41], v24, off offset:64
	global_store_short v[40:41], v9, off offset:256
	global_store_short v[40:41], v25, off offset:320
	global_store_short v[40:41], v10, off offset:512
	global_store_short v[40:41], v26, off offset:576
	global_store_short v[40:41], v11, off offset:768
	global_store_short v[40:41], v27, off offset:832
	global_store_short v[40:41], v12, off offset:2048
	global_store_short v[40:41], v28, off offset:2112
	global_store_short v[40:41], v13, off offset:2304
	global_store_short v[40:41], v29, off offset:2368
	global_store_short v[40:41], v14, off offset:2560
	global_store_short v[40:41], v30, off offset:2624
	global_store_short v[40:41], v15, off offset:2816
	global_store_short v[40:41], v31, off offset:2880
	s_waitcnt lgkmcnt(0)
	s_barrier
	s_cmpk_gt_i32 s11, 0x7ff
	s_cbranch_scc0 .LBB0_440
